# phase5 (wkv outputs) item loop software-pipelined: next item's 22 data loads issued into a second register set before the current item's math, copied at the loop top; group-norm parameter loads all is
# speedup vs baseline: 1.0041x; 1.0023x over previous
.LBB0_1116:
	s_or_b64 exec, exec, s[0:1]
	v_mov_b32_e32 v2, v174
	s_waitcnt lgkmcnt(0)
	v_mov_b32_e32 v0, v174
	s_barrier
	v_readlane_b32 s0, v241, 16
	v_ashrrev_i32_e32 v8, 6, v0
	s_nop 0
	v_add_u32_e32 v1, s0, v8
	s_movk_i32 s0, 0x4000
	v_cmp_gt_i32_e32 vcc, s0, v1
	s_mov_b64 s[0:1], exec
	v_readlane_b32 s68, v241, 49
	v_readlane_b32 s36, v240, 1
	s_and_b64 s[2:3], s[0:1], vcc
	v_readlane_b32 s72, v241, 53
	v_readlane_b32 s73, v241, 54
	v_readlane_b32 s74, v241, 55
	v_readlane_b32 s75, v241, 56
	v_readlane_b32 s42, v240, 7
	v_readlane_b32 s43, v240, 8
	v_readlane_b32 s50, v240, 15
	v_readlane_b32 s51, v240, 16
	v_readlane_b32 s69, v241, 50
	v_readlane_b32 s70, v241, 51
	v_readlane_b32 s71, v241, 52
	v_readlane_b32 s76, v241, 57
	v_readlane_b32 s77, v241, 58
	v_readlane_b32 s78, v241, 59
	v_readlane_b32 s79, v241, 60
	v_readlane_b32 s80, v241, 61
	v_readlane_b32 s81, v241, 62
	v_readlane_b32 s82, v241, 63
	v_readlane_b32 s83, v240, 0
	v_readlane_b32 s37, v240, 2
	v_readlane_b32 s38, v240, 3
	v_readlane_b32 s39, v240, 4
	v_readlane_b32 s40, v240, 5
	v_readlane_b32 s41, v240, 6
	v_readlane_b32 s44, v240, 9
	v_readlane_b32 s45, v240, 10
	v_readlane_b32 s46, v240, 11
	v_readlane_b32 s47, v240, 12
	v_readlane_b32 s48, v240, 13
	v_readlane_b32 s49, v240, 14
	s_mov_b64 exec, s[2:3]
	s_cbranch_execz .LBB0_1119
	v_and_b32_e32 v6, 64, v175
	v_xor_b32_e32 v5, 16, v175
	v_add_u32_e32 v6, 64, v6
	v_cmp_lt_i32_e32 vcc, v5, v6
	v_xor_b32_e32 v7, 32, v175
	v_and_b32_e32 v0, 15, v2
	v_bfe_u32 v2, v2, 4, 2
	v_cndmask_b32_e32 v5, v175, v5, vcc
	v_cmp_lt_i32_e32 vcc, v7, v6
	v_mov_b32_e32 v3, 0
	v_lshlrev_b32_e32 v4, 2, v2
	v_lshlrev_b32_e32 v10, 3, v2
	v_cndmask_b32_e32 v6, v175, v7, vcc
	v_lshlrev_b32_e32 v2, 4, v2
	v_lshlrev_b32_e32 v16, 2, v6
	v_lshl_add_u64 v[6:7], s[62:63], 0, v[2:3]
	v_lshlrev_b32_e32 v2, 7, v0
	s_mov_b64 s[68:69], s[72:73]
	v_lshl_add_u64 v[6:7], v[6:7], 0, v[2:3]
	v_lshlrev_b32_e32 v2, 4, v8
	s_mov_b64 s[70:71], s[74:75]
	s_mov_b64 s[22:23], s[50:51]
	v_lshlrev_b32_e32 v5, 2, v5
	s_lshl_b32 s2, s88, 3
	v_lshl_add_u32 v17, s90, 7, v2
	s_lshl_b32 s3, s88, 7
	s_mov_b64 s[4:5], 0
	v_lshlrev_b32_e32 v8, 1, v10
	v_mov_b32_e32 v9, v3
	s_movk_i32 s6, 0x1c0
	v_lshlrev_b32_e32 v10, 1, v4
	v_mov_b32_e32 v11, v3
	s_movk_i32 s7, 0x1800
	v_mov_b64_e32 v[12:13], s[42:43]
	s_movk_i32 s8, 0x1000
	v_mov_b32_e32 v18, 0x3a27c5ac
	s_mov_b32 s9, 0x800000
	s_movk_i32 s10, 0x3fff
	v_ashrrev_i32_e32 v208, 2, v1
	v_ashrrev_i32_e32 v210, 11, v1
	v_and_b32_e32 v212, 48, v17
	v_lshrrev_b32_e32 v213, 2, v1
	v_ashrrev_i32_e32 v209, 31, v208
	v_ashrrev_i32_e32 v211, 31, v210
	v_lshlrev_b32_e32 v214, 6, v208
	v_or_b32_e32 v215, v212, v0
	v_and_or_b32 v216, v213, s6, v4
	v_lshlrev_b64 v[208:209], 13, v[208:209]
	v_lshlrev_b64 v[218:219], 12, v[210:211]
	v_and_b32_e32 v214, 0xfc0, v214
	v_lshlrev_b32_e32 v220, 7, v215
	v_mov_b32_e32 v221, 0
	v_lshlrev_b32_e32 v170, 2, v216
	v_lshl_add_u64 v[222:223], s[58:59], 0, v[208:209]
	v_lshl_add_u64 v[224:225], s[60:61], 0, v[208:209]
	v_lshl_add_u64 v[208:209], v[6:7], 0, v[208:209]
	v_or3_b32 v212, v218, v214, v212
	v_lshl_add_u64 v[222:223], v[222:223], 0, v[220:221]
	v_lshl_add_u64 v[224:225], v[224:225], 0, v[220:221]
	v_lshlrev_b32_e32 v220, 1, v216
	global_load_dwordx4 v[120:123], v[208:209], off
	global_load_dwordx4 v[124:127], v[208:209], off offset:64
	global_load_dwordx4 v[128:131], v[208:209], off offset:2048
	global_load_dwordx4 v[132:135], v[208:209], off offset:2112
	v_add_co_u32_e32 v226, vcc, s8, v208
	v_or_b32_e32 v218, v212, v0
	s_nop 0
	v_addc_co_u32_e32 v227, vcc, 0, v209, vcc
	v_lshl_add_u64 v[228:229], v[222:223], 0, v[8:9]
	v_lshl_add_u64 v[230:231], v[224:225], 0, v[10:11]
	v_lshlrev_b64 v[232:233], 10, v[218:219]
	v_mad_u64_u32 v[234:235], s[12:13], v218, s7, v[12:13]
	global_load_dwordx4 v[136:139], v[226:227], off
	global_load_dwordx4 v[140:143], v[226:227], off offset:64
	global_load_dwordx4 v[144:147], v[226:227], off offset:2048
	global_load_dwordx4 v[148:151], v[226:227], off offset:2112
	v_lshlrev_b64 v[168:169], 11, v[218:219]
	global_load_dwordx2 v[160:161], v[230:231], off
	global_load_dwordx2 v[162:163], v[230:231], off offset:32
	global_load_dwordx4 v[152:155], v[228:229], off
	global_load_dwordx2 v[164:165], v[230:231], off offset:64
	global_load_dwordx2 v[166:167], v[230:231], off offset:96
	global_load_dwordx4 v[156:159], v[228:229], off offset:64
	v_lshl_add_u64 v[232:233], s[52:53], 0, v[232:233]
	v_mad_i32_i24 v235, v211, s7, v235
	v_lshl_add_u64 v[236:237], v[232:233], 0, v[220:221]
	v_lshl_add_u64 v[238:239], v[234:235], 0, v[220:221]
	global_load_dwordx2 v[176:177], v[236:237], off
	global_load_dwordx2 v[178:179], v[236:237], off offset:32
	global_load_dwordx2 v[180:181], v[236:237], off offset:64
	global_load_dwordx2 v[182:183], v[236:237], off offset:96
	global_load_dwordx2 v[184:185], v[238:239], off offset:1024
	global_load_dwordx2 v[186:187], v[238:239], off offset:1056
	global_load_dwordx2 v[188:189], v[238:239], off offset:1088
	global_load_dwordx2 v[190:191], v[238:239], off offset:1120
	v_lshl_add_u64 v[168:169], s[22:23], 0, v[168:169]
	v_lshl_add_u64 v[168:169], v[168:169], 0, v[220:221]
	s_waitcnt vmcnt(0)
.LBB0_1118:
	s_waitcnt vmcnt(4)
	v_mov_b64_e32 v[28:29], v[120:121]
	v_mov_b64_e32 v[30:31], v[122:123]
	v_mov_b64_e32 v[32:33], v[124:125]
	v_mov_b64_e32 v[34:35], v[126:127]
	v_mov_b64_e32 v[36:37], v[128:129]
	v_mov_b64_e32 v[38:39], v[130:131]
	v_mov_b64_e32 v[40:41], v[132:133]
	v_mov_b64_e32 v[42:43], v[134:135]
	v_mov_b64_e32 v[44:45], v[136:137]
	v_mov_b64_e32 v[46:47], v[138:139]
	v_mov_b64_e32 v[48:49], v[140:141]
	v_mov_b64_e32 v[50:51], v[142:143]
	v_mov_b64_e32 v[52:53], v[144:145]
	v_mov_b64_e32 v[54:55], v[146:147]
	v_mov_b64_e32 v[56:57], v[148:149]
	v_mov_b64_e32 v[58:59], v[150:151]
	v_mov_b64_e32 v[60:61], v[152:153]
	v_mov_b64_e32 v[62:63], v[154:155]
	v_mov_b64_e32 v[64:65], v[156:157]
	v_mov_b64_e32 v[66:67], v[158:159]
	v_mov_b64_e32 v[74:75], v[160:161]
	v_mov_b64_e32 v[76:77], v[162:163]
	v_mov_b64_e32 v[78:79], v[164:165]
	v_mov_b64_e32 v[80:81], v[166:167]
	v_mov_b64_e32 v[192:193], v[176:177]
	v_mov_b64_e32 v[194:195], v[178:179]
	v_mov_b64_e32 v[196:197], v[180:181]
	v_mov_b64_e32 v[198:199], v[182:183]
	v_mov_b64_e32 v[200:201], v[184:185]
	v_mov_b64_e32 v[202:203], v[186:187]
	v_mov_b64_e32 v[204:205], v[188:189]
	v_mov_b64_e32 v[206:207], v[190:191]
	v_mov_b64_e32 v[14:15], v[168:169]
	v_mov_b32_e32 v94, v170
	global_load_dwordx4 v[20:23], v94, s[68:69]
	global_load_dwordx4 v[24:27], v94, s[70:71]
	global_load_dwordx4 v[96:99], v94, s[68:69] offset:64
	global_load_dwordx4 v[100:103], v94, s[70:71] offset:64
	global_load_dwordx4 v[104:107], v94, s[68:69] offset:128
	global_load_dwordx4 v[108:111], v94, s[70:71] offset:128
	global_load_dwordx4 v[112:115], v94, s[68:69] offset:192
	global_load_dwordx4 v[116:119], v94, s[70:71] offset:192
	v_add_u32_e32 v1, s2, v1
	v_add_u32_e32 v17, s3, v17
	v_cmp_lt_i32_e32 vcc, s10, v1
	s_cbranch_vccnz .Lp5_last_item
	v_ashrrev_i32_e32 v208, 2, v1
	v_ashrrev_i32_e32 v210, 11, v1
	v_and_b32_e32 v212, 48, v17
	v_lshrrev_b32_e32 v213, 2, v1
	v_ashrrev_i32_e32 v209, 31, v208
	v_ashrrev_i32_e32 v211, 31, v210
	v_lshlrev_b32_e32 v214, 6, v208
	v_or_b32_e32 v215, v212, v0
	v_and_or_b32 v216, v213, s6, v4
	v_lshlrev_b64 v[208:209], 13, v[208:209]
	v_lshlrev_b64 v[218:219], 12, v[210:211]
	v_and_b32_e32 v214, 0xfc0, v214
	v_lshlrev_b32_e32 v220, 7, v215
	v_mov_b32_e32 v221, 0
	v_lshlrev_b32_e32 v170, 2, v216
	v_lshl_add_u64 v[222:223], s[58:59], 0, v[208:209]
	v_lshl_add_u64 v[224:225], s[60:61], 0, v[208:209]
	v_lshl_add_u64 v[208:209], v[6:7], 0, v[208:209]
	v_or3_b32 v212, v218, v214, v212
	v_lshl_add_u64 v[222:223], v[222:223], 0, v[220:221]
	v_lshl_add_u64 v[224:225], v[224:225], 0, v[220:221]
	v_lshlrev_b32_e32 v220, 1, v216
	global_load_dwordx4 v[120:123], v[208:209], off
	global_load_dwordx4 v[124:127], v[208:209], off offset:64
	global_load_dwordx4 v[128:131], v[208:209], off offset:2048
	global_load_dwordx4 v[132:135], v[208:209], off offset:2112
	v_add_co_u32_e32 v226, vcc, s8, v208
	v_or_b32_e32 v218, v212, v0
	s_nop 0
	v_addc_co_u32_e32 v227, vcc, 0, v209, vcc
	v_lshl_add_u64 v[228:229], v[222:223], 0, v[8:9]
	v_lshl_add_u64 v[230:231], v[224:225], 0, v[10:11]
	v_lshlrev_b64 v[232:233], 10, v[218:219]
	v_mad_u64_u32 v[234:235], s[12:13], v218, s7, v[12:13]
	global_load_dwordx4 v[136:139], v[226:227], off
	global_load_dwordx4 v[140:143], v[226:227], off offset:64
	global_load_dwordx4 v[144:147], v[226:227], off offset:2048
	global_load_dwordx4 v[148:151], v[226:227], off offset:2112
	v_lshlrev_b64 v[168:169], 11, v[218:219]
	global_load_dwordx2 v[160:161], v[230:231], off
	global_load_dwordx2 v[162:163], v[230:231], off offset:32
	global_load_dwordx4 v[152:155], v[228:229], off
	global_load_dwordx2 v[164:165], v[230:231], off offset:64
	global_load_dwordx2 v[166:167], v[230:231], off offset:96
	global_load_dwordx4 v[156:159], v[228:229], off offset:64
	v_lshl_add_u64 v[232:233], s[52:53], 0, v[232:233]
	v_mad_i32_i24 v235, v211, s7, v235
	v_lshl_add_u64 v[236:237], v[232:233], 0, v[220:221]
	v_lshl_add_u64 v[238:239], v[234:235], 0, v[220:221]
	global_load_dwordx2 v[176:177], v[236:237], off
	global_load_dwordx2 v[178:179], v[236:237], off offset:32
	global_load_dwordx2 v[180:181], v[236:237], off offset:64
	global_load_dwordx2 v[182:183], v[236:237], off offset:96
	global_load_dwordx2 v[184:185], v[238:239], off offset:1024
	global_load_dwordx2 v[186:187], v[238:239], off offset:1056
	global_load_dwordx2 v[188:189], v[238:239], off offset:1088
	global_load_dwordx2 v[190:191], v[238:239], off offset:1120
	v_lshl_add_u64 v[168:169], s[22:23], 0, v[168:169]
	v_lshl_add_u64 v[168:169], v[168:169], 0, v[220:221]
	s_branch .Lp5_math

.Lp5_math:
	v_lshlrev_b32_e32 v68, 16, v74
	v_and_b32_e32 v69, 0xffff0000, v74
	v_lshlrev_b32_e32 v70, 16, v75
	v_and_b32_e32 v71, 0xffff0000, v75
	s_nop 0
	v_lshlrev_b32_e32 v72, 16, v76
	v_and_b32_e32 v73, 0xffff0000, v76
	v_lshlrev_b32_e32 v74, 16, v77
	v_and_b32_e32 v75, 0xffff0000, v77
	s_nop 0
	v_mfma_f32_16x16x32_bf16 v[28:31], v[28:31], v[60:63], v[68:71]
	s_nop 0
	v_lshlrev_b32_e32 v19, 16, v192
	v_and_b32_e32 v77, 0xffff0000, v193
	s_nop 0
	v_lshlrev_b32_e32 v76, 16, v201
	v_mfma_f32_16x16x32_bf16 v[36:39], v[36:39], v[60:63], v[72:75]
	v_lshlrev_b32_e32 v68, 16, v78
	v_and_b32_e32 v69, 0xffff0000, v78
	v_lshlrev_b32_e32 v70, 16, v79
	v_and_b32_e32 v71, 0xffff0000, v79
	v_lshlrev_b32_e32 v72, 16, v80
	v_and_b32_e32 v73, 0xffff0000, v80
	v_lshlrev_b32_e32 v74, 16, v81
	v_and_b32_e32 v75, 0xffff0000, v81
	v_mfma_f32_16x16x32_bf16 v[44:47], v[44:47], v[60:63], v[68:71]
	v_and_b32_e32 v78, 0xffff0000, v201
	v_mfma_f32_16x16x32_bf16 v[52:55], v[52:55], v[60:63], v[72:75]
	s_nop 2
	v_and_b32_e32 v73, 0xffff0000, v192
	v_lshlrev_b32_e32 v75, 16, v193
	v_mfma_f32_16x16x32_bf16 v[28:31], v[32:35], v[64:67], v[28:31]
	v_lshlrev_b32_e32 v72, 16, v200
	v_and_b32_e32 v74, 0xffff0000, v200
	s_nop 0
	v_mfma_f32_16x16x32_bf16 v[32:35], v[40:43], v[64:67], v[36:39]
	v_mfma_f32_16x16x32_bf16 v[36:39], v[48:51], v[64:67], v[44:47]
	s_nop 2
	v_mov_b32_e32 v48, v30
	s_nop 2
	v_mov_b32_e32 v49, v34
	v_mov_b32_e32 v50, v31
	v_mfma_f32_16x16x32_bf16 v[40:43], v[56:59], v[64:67], v[52:55]
	v_mov_b32_e32 v44, v28
	v_mov_b32_e32 v45, v32
	v_mov_b32_e32 v46, v29
	v_mov_b32_e32 v47, v33
	v_pk_add_f32 v[44:45], v[44:45], v[46:47]
	v_mov_b32_e32 v51, v35
	v_mov_b32_e32 v46, v36
	s_nop 0
	v_mov_b32_e32 v47, v40
	v_mov_b32_e32 v52, v37
	v_mov_b32_e32 v53, v41
	v_pk_add_f32 v[44:45], v[48:49], v[44:45]
	v_mov_b32_e32 v54, v38
	v_mov_b32_e32 v55, v42
	v_pk_add_f32 v[46:47], v[46:47], v[52:53]
	v_pk_add_f32 v[44:45], v[50:51], v[44:45]
	v_mov_b32_e32 v56, v39
	v_mov_b32_e32 v57, v43
	v_pk_add_f32 v[46:47], v[54:55], v[46:47]
	v_add_f32_e32 v2, 0, v44
	v_pk_add_f32 v[46:47], v[56:57], v[46:47]
	v_add_f32_e32 v2, v2, v45
	v_add_f32_e32 v2, v2, v46
	v_add_f32_e32 v2, v2, v47
	ds_bpermute_b32 v44, v5, v2
	s_waitcnt lgkmcnt(0)
	v_add_f32_e32 v2, v2, v44
	ds_bpermute_b32 v44, v16, v2
	s_waitcnt lgkmcnt(0)
	v_add_f32_e32 v44, v2, v44
	v_fmamk_f32 v49, v44, 0xbc800000, v29
	v_fmamk_f32 v48, v44, 0xbc800000, v28
	v_mul_f32_e32 v52, v49, v49
	v_fmamk_f32 v30, v44, 0xbc800000, v30
	v_fmac_f32_e32 v52, v48, v48
	v_fmac_f32_e32 v31, 0xbc800000, v44
	v_fmac_f32_e32 v52, v30, v30
	v_fmamk_f32 v50, v44, 0xbc800000, v32
	v_fmac_f32_e32 v52, v31, v31
	v_fmamk_f32 v51, v44, 0xbc800000, v33
	v_fmac_f32_e32 v52, v50, v50
	v_mul_f32_e32 v2, 0x3c800000, v44
	v_fmamk_f32 v34, v44, 0xbc800000, v34
	v_fmac_f32_e32 v52, v51, v51
	v_fmac_f32_e32 v35, 0xbc800000, v44
	v_pk_add_f32 v[28:29], v[36:37], v[2:3] op_sel_hi:[1,0] neg_lo:[0,1] neg_hi:[0,1]
	v_fmac_f32_e32 v52, v34, v34
	v_pk_add_f32 v[36:37], v[40:41], v[2:3] op_sel_hi:[1,0] neg_lo:[0,1] neg_hi:[0,1]
	v_pk_mul_f32 v[40:41], v[28:29], v[28:29]
	v_fmac_f32_e32 v52, v35, v35
	v_pk_add_f32 v[32:33], v[38:39], v[2:3] op_sel_hi:[1,0] neg_lo:[0,1] neg_hi:[0,1]
	v_pk_add_f32 v[38:39], v[42:43], v[2:3] op_sel_hi:[1,0] neg_lo:[0,1] neg_hi:[0,1]
	v_add_f32_e32 v2, v40, v52
	v_pk_mul_f32 v[42:43], v[32:33], v[32:33]
	v_add_f32_e32 v2, v41, v2
	v_add_f32_e32 v2, v42, v2
	v_pk_mul_f32 v[44:45], v[36:37], v[36:37]
	v_add_f32_e32 v2, v43, v2
	v_add_f32_e32 v2, v44, v2
	v_pk_mul_f32 v[46:47], v[38:39], v[38:39]
	v_add_f32_e32 v2, v45, v2
	v_add_f32_e32 v2, v46, v2
	v_add_f32_e32 v2, v47, v2
	ds_bpermute_b32 v40, v5, v2
	s_nop 0
	v_and_b32_e32 v43, 0xffff0000, v195
	v_lshlrev_b32_e32 v42, 16, v203
	v_and_b32_e32 v44, 0xffff0000, v203
	s_waitcnt lgkmcnt(0)
	v_add_f32_e32 v2, v2, v40
	ds_bpermute_b32 v40, v16, v2
	s_waitcnt lgkmcnt(0)
	v_add_f32_e32 v2, v2, v40
	v_fmamk_f32 v2, v2, 0x3c800000, v18
	v_mul_f32_e32 v40, 0x4b800000, v2
	v_cmp_gt_f32_e32 vcc, s9, v2
	s_nop 1
	v_cndmask_b32_e32 v2, v2, v40, vcc
	v_rsq_f32_e32 v2, v2
	s_nop 0
	v_mul_f32_e32 v40, 0x45800000, v2
	v_cndmask_b32_e32 v2, v2, v40, vcc
	v_mul_f32_e32 v40, v48, v2
	v_mul_f32_e32 v41, v49, v2
	v_mul_f32_e32 v30, v30, v2
	v_mul_f32_e32 v31, v31, v2
	s_waitcnt vmcnt(22)
	v_fma_f32 v20, v20, v40, v24
	v_fma_f32 v21, v21, v41, v25
	v_fma_f32 v22, v22, v30, v26
	v_fmac_f32_e32 v27, v23, v31
	v_add_f32_e32 v19, v20, v19
	v_add_f32_e32 v20, v21, v73
	v_add_f32_e32 v21, v22, v75
	v_add_f32_e32 v22, v27, v77
	v_mul_f32_e32 v19, v19, v72
	v_mul_f32_e32 v20, v20, v74
	v_mul_f32_e32 v21, v21, v76
	v_mul_f32_e32 v22, v22, v78
	v_cvt_pk_bf16_f32 v20, v19, v20
	v_cvt_pk_bf16_f32 v21, v21, v22
	global_store_dwordx2 v[14:15], v[20:21], off offset:1024
	v_mul_f32_e32 v45, v50, v2
	v_mul_f32_e32 v46, v51, v2
	v_mul_f32_e32 v34, v34, v2
	v_mul_f32_e32 v35, v35, v2
	v_lshlrev_b32_e32 v19, 16, v194
	v_and_b32_e32 v31, 0xffff0000, v194
	v_lshlrev_b32_e32 v41, 16, v195
	v_lshlrev_b32_e32 v30, 16, v202
	v_and_b32_e32 v40, 0xffff0000, v202
	v_mul_f32_e32 v28, v28, v2
	v_mul_f32_e32 v29, v29, v2
	v_mul_f32_e32 v32, v32, v2
	v_mul_f32_e32 v33, v33, v2
	v_cmp_lt_i32_e32 vcc, s10, v1
	s_or_b64 s[4:5], vcc, s[4:5]
	v_fma_f32 v20, v96, v45, v100
	v_fma_f32 v21, v97, v46, v101
	v_fma_f32 v22, v98, v34, v102
	v_fma_f32 v27, v99, v35, v103
	v_add_f32_e32 v19, v20, v19
	v_add_f32_e32 v20, v21, v31
	v_add_f32_e32 v21, v22, v41
	v_add_f32_e32 v22, v27, v43
	v_mul_f32_e32 v19, v19, v30
	v_mul_f32_e32 v20, v20, v40
	v_mul_f32_e32 v21, v21, v42
	v_mul_f32_e32 v22, v22, v44
	v_cvt_pk_bf16_f32 v20, v19, v20
	v_cvt_pk_bf16_f32 v21, v21, v22
	global_store_dwordx2 v[14:15], v[20:21], off offset:1056
	v_lshlrev_b32_e32 v19, 16, v196
	v_and_b32_e32 v31, 0xffff0000, v196
	v_lshlrev_b32_e32 v35, 16, v197
	v_and_b32_e32 v41, 0xffff0000, v197
	v_lshlrev_b32_e32 v30, 16, v204
	v_and_b32_e32 v34, 0xffff0000, v204
	v_lshlrev_b32_e32 v40, 16, v205
	v_and_b32_e32 v42, 0xffff0000, v205
	v_fma_f32 v20, v104, v28, v108
	v_fma_f32 v21, v105, v29, v109
	v_fma_f32 v22, v106, v32, v110
	v_fma_f32 v27, v107, v33, v111
	v_add_f32_e32 v19, v20, v19
	v_add_f32_e32 v20, v21, v31
	v_add_f32_e32 v21, v22, v35
	v_add_f32_e32 v22, v27, v41
	v_mul_f32_e32 v19, v19, v30
	v_mul_f32_e32 v20, v20, v34
	v_mul_f32_e32 v21, v21, v40
	v_mul_f32_e32 v22, v22, v42
	v_cvt_pk_bf16_f32 v20, v19, v20
	v_cvt_pk_bf16_f32 v21, v21, v22
	global_store_dwordx2 v[14:15], v[20:21], off offset:1088
	v_mul_f32_e32 v35, v36, v2
	v_mul_f32_e32 v36, v37, v2
	v_mul_f32_e32 v37, v38, v2
	v_mul_f32_e32 v2, v39, v2
	v_lshlrev_b32_e32 v19, 16, v198
	v_and_b32_e32 v29, 0xffff0000, v198
	v_lshlrev_b32_e32 v31, 16, v199
	v_and_b32_e32 v33, 0xffff0000, v199
	v_lshlrev_b32_e32 v28, 16, v206
	v_and_b32_e32 v30, 0xffff0000, v206
	v_lshlrev_b32_e32 v32, 16, v207
	v_and_b32_e32 v34, 0xffff0000, v207
	v_fma_f32 v20, v112, v35, v116
	v_fma_f32 v21, v36, v113, v117
	v_fma_f32 v22, v37, v114, v118
	v_fma_f32 v27, v2, v115, v119
	v_add_f32_e32 v2, v20, v19
	v_add_f32_e32 v19, v21, v29
	v_add_f32_e32 v20, v22, v31
	v_add_f32_e32 v21, v27, v33
	v_mul_f32_e32 v2, v2, v28
	v_mul_f32_e32 v19, v19, v30
	v_mul_f32_e32 v22, v20, v32
	v_mul_f32_e32 v21, v21, v34
	v_cvt_pk_bf16_f32 v20, v2, v19
	v_cvt_pk_bf16_f32 v21, v22, v21
	global_store_dwordx2 v[14:15], v[20:21], off offset:1120
	s_andn2_b64 exec, exec, s[4:5]
	s_cbranch_execnz .LBB0_1118
